# GEMM units: removed the redundant first accumulator-zeroing block (128 v_mov per unit; the loop preheader zeroes again), 6 GEMM sites; stacked on v14
# speedup vs baseline: 1.0155x; 1.0087x over previous
; #define PG8_GOFFS(slot_) do { _Pragma("unroll") for (int _i = 0; _i < 2; ++_i) { int R, C; stage_rc(tid * 16 + _i * 8192, R, C); _Pragma("unroll") for (int _h = 0; _h < 2; ++_h) { \
;         unsigned t_ = gtab[(slot_) * 256 + R + 128 * _h]; t_ = t_ < (unsigned)(T - 1) ? t_ : (unsigned)(T - 1); voffA[_h][_i] = (t_ * (unsigned)K + (unsigned)C) * 2u; } } } while (0)
; #define PG8_STAGE(bufoff, gbase, voff) do { _Pragma("unroll") for (int _i = 0; _i < 2; ++_i) \
;         __builtin_amdgcn_global_load_lds((const unsigned*)((const char*)(gbase) + (voff)[_i]), (LAS unsigned*)(lds + (bufoff) + ldsw + _i * 8192), 16, 0, 0); } while (0)
; #define PG8_STAGE_A1(bufoff, gbase) do { if (Epi::GATHER) PG8_STAGE(bufoff, gbase, voffA[1]); else PG8_STAGE(bufoff, (gbase) + hstep, voffA[0]); } while (0)
; #define PG8_WAIT_V(n) asm volatile("s_waitcnt vmcnt(" #n ")" ::: "memory")
; #define PG8_BAR __builtin_amdgcn_s_barrier()
; template <class Epi, class Sched>
; __device__ __forceinline__ void gemm_phase(const int tid, LAS unsigned char* lds, const bf16* Aop, const bf16* Bop, const int K_, const Sched& S, const Epi& E, const bf16* Aop1 = nullptr, const bf16* Bop1 = nullptr) {
;     ...
;     f32x4 acc[2][2][4][2];
; #pragma unroll
;     for (int a = 0; a < 2; ++a)
; #pragma unroll
;         for (int b = 0; b < 2; ++b)
; #pragma unroll
;             for (int m = 0; m < 4; ++m)
; #pragma unroll
;                 for (int n = 0; n < 2; ++n) acc[a][b][m][n] = (f32x4){0.f, 0.f, 0.f, 0.f};
;     bf16x8 At[4][2], B0[2][2], B1[2][2];
;     if (Epi::GATHER) { if (tid < 256) gtab[tid] = (unsigned)E.tok_at(cur.pm * 256 + tid); __syncthreads(); PG8_GOFFS(0); }
;     const char* cA = (const char*)((Aop1 && cur.sel) ? Aop1 : Aop) + (Epi::GATHER ? (size_t)0 : (size_t)cur.pm * tstep); const char* cB = (const char*)((Bop1 && cur.sel) ? Bop1 : Bop) + (size_t)cur.pb * tstep;
;     PG8_STAGE(PG8_SB(0, 0), cB, voffB); PG8_STAGE(PG8_SB(0, 1), cB + hstep, voffB); PG8_STAGE(PG8_SA(0, 0), cA, voffA[0]); PG8_STAGE_A1(PG8_SA(0, 1), cA);
;     if (wr == 1) PG8_BAR;
;     PG8_WAIT_V(2); PG8_BAR;
;     PG8_STAGE(PG8_SB(1, 0), cB + kstep, voffB); PG8_STAGE(PG8_SA(1, 0), cA + kstep, voffA[0]); PG8_STAGE(PG8_SB(1, 1), cB + hstep + kstep, voffB);
;     PG8_WAIT_V(6); PG8_BAR;
.LBB0_129:
	v_mov_b32_e32 v143, 0
	s_andn2_b64 vcc, exec, s[18:19]
	s_cbranch_vccnz .LBB0_133
	s_add_u32 s26, s26, 0x80
	s_addc_u32 s27, s27, 0
	s_add_u32 s11, s42, 0x100
	v_mov_b32_e32 v4, 0
	v_mov_b64_e32 v[180:181], v[178:179]
	v_mov_b64_e32 v[178:179], v[176:177]
	v_mov_b64_e32 v[176:177], v[190:191]
	v_mov_b32_e32 v205, 0x7f800000
	v_mov_b32_e32 v203, 0x3ecc95a3
	v_mov_b32_e32 v200, 1
	v_mov_b64_e32 v[226:227], 0x100
	s_addc_u32 s42, s43, 0
	s_mov_b32 s40, 0
	v_mov_b32_e32 v5, v4
	v_mov_b32_e32 v6, v4
	v_mov_b32_e32 v7, v4
	v_mov_b32_e32 v8, v4
	v_mov_b32_e32 v9, v4
	v_mov_b32_e32 v10, v4
	v_mov_b32_e32 v11, v4
	v_mov_b32_e32 v20, v4
	v_mov_b32_e32 v21, v4
	v_mov_b32_e32 v22, v4
	v_mov_b32_e32 v23, v4
	v_mov_b32_e32 v24, v4
	v_mov_b32_e32 v25, v4
	v_mov_b32_e32 v26, v4
	v_mov_b32_e32 v27, v4
	v_mov_b32_e32 v36, v4
	v_mov_b32_e32 v37, v4
	v_mov_b32_e32 v38, v4
	v_mov_b32_e32 v39, v4
	v_mov_b32_e32 v40, v4
	v_mov_b32_e32 v41, v4
	v_mov_b32_e32 v42, v4
	v_mov_b32_e32 v43, v4
	v_mov_b32_e32 v52, v4
	v_mov_b32_e32 v53, v4
	v_mov_b32_e32 v54, v4
	v_mov_b32_e32 v55, v4
	v_mov_b32_e32 v56, v4
	v_mov_b32_e32 v57, v4
	v_mov_b32_e32 v58, v4
	v_mov_b32_e32 v59, v4
	v_mov_b32_e32 v12, v4
	v_mov_b32_e32 v13, v4
	v_mov_b32_e32 v14, v4
	v_mov_b32_e32 v15, v4
	v_mov_b32_e32 v16, v4
	v_mov_b32_e32 v17, v4
	v_mov_b32_e32 v18, v4
	v_mov_b32_e32 v19, v4
	v_mov_b32_e32 v28, v4
	v_mov_b32_e32 v29, v4
	v_mov_b32_e32 v30, v4
	v_mov_b32_e32 v31, v4
	v_mov_b32_e32 v32, v4
	v_mov_b32_e32 v33, v4
	v_mov_b32_e32 v34, v4
	v_mov_b32_e32 v35, v4
	v_mov_b32_e32 v44, v4
	v_mov_b32_e32 v45, v4
	v_mov_b32_e32 v46, v4
	v_mov_b32_e32 v47, v4
	v_mov_b32_e32 v48, v4
	v_mov_b32_e32 v49, v4
	v_mov_b32_e32 v50, v4
	v_mov_b32_e32 v51, v4
	v_mov_b32_e32 v64, v4
	v_mov_b32_e32 v65, v4
	v_mov_b32_e32 v66, v4
	v_mov_b32_e32 v67, v4
	v_mov_b32_e32 v72, v4
	v_mov_b32_e32 v73, v4
	v_mov_b32_e32 v74, v4
	v_mov_b32_e32 v75, v4
	v_mov_b32_e32 v84, v4
	v_mov_b32_e32 v85, v4
	v_mov_b32_e32 v86, v4
	v_mov_b32_e32 v87, v4
	v_mov_b32_e32 v88, v4
	v_mov_b32_e32 v89, v4
	v_mov_b32_e32 v90, v4
	v_mov_b32_e32 v91, v4
	v_mov_b32_e32 v100, v4
	v_mov_b32_e32 v101, v4
	v_mov_b32_e32 v102, v4
	v_mov_b32_e32 v103, v4
	v_mov_b32_e32 v104, v4
	v_mov_b32_e32 v105, v4
	v_mov_b32_e32 v106, v4
	v_mov_b32_e32 v107, v4
	v_mov_b32_e32 v116, v4
	v_mov_b32_e32 v117, v4
	v_mov_b32_e32 v118, v4
	v_mov_b32_e32 v119, v4
	v_mov_b32_e32 v120, v4
	v_mov_b32_e32 v121, v4
	v_mov_b32_e32 v122, v4
	v_mov_b32_e32 v123, v4
	v_mov_b32_e32 v132, v4
	v_mov_b32_e32 v133, v4
	v_mov_b32_e32 v134, v4
	v_mov_b32_e32 v135, v4
	v_mov_b32_e32 v136, v4
	v_mov_b32_e32 v137, v4
	v_mov_b32_e32 v138, v4
	v_mov_b32_e32 v139, v4
	v_mov_b32_e32 v92, v4
	v_mov_b32_e32 v93, v4
	v_mov_b32_e32 v94, v4
	v_mov_b32_e32 v95, v4
	v_mov_b32_e32 v96, v4
	v_mov_b32_e32 v97, v4
	v_mov_b32_e32 v98, v4
	v_mov_b32_e32 v99, v4
	v_mov_b32_e32 v108, v4
	v_mov_b32_e32 v109, v4
	v_mov_b32_e32 v110, v4
	v_mov_b32_e32 v111, v4
	v_mov_b32_e32 v112, v4
	v_mov_b32_e32 v113, v4
	v_mov_b32_e32 v114, v4
	v_mov_b32_e32 v115, v4
	v_mov_b32_e32 v124, v4
	v_mov_b32_e32 v125, v4
	v_mov_b32_e32 v126, v4
	v_mov_b32_e32 v127, v4
	v_mov_b32_e32 v128, v4
	v_mov_b32_e32 v129, v4
	v_mov_b32_e32 v130, v4
	v_mov_b32_e32 v131, v4
	v_mov_b32_e32 v144, v4
	v_mov_b32_e32 v145, v4
	v_mov_b32_e32 v146, v4
	v_mov_b32_e32 v147, v4
	v_mov_b32_e32 v140, v4
	v_mov_b32_e32 v141, v4
	v_mov_b32_e32 v142, v4
	v_mov_b32_e32 v143, v4

; #define PG8_GOFFS(slot_) do { _Pragma("unroll") for (int _i = 0; _i < 2; ++_i) { int R, C; stage_rc(tid * 16 + _i * 8192, R, C); _Pragma("unroll") for (int _h = 0; _h < 2; ++_h) { \
;         unsigned t_ = gtab[(slot_) * 256 + R + 128 * _h]; t_ = t_ < (unsigned)(T - 1) ? t_ : (unsigned)(T - 1); voffA[_h][_i] = (t_ * (unsigned)K + (unsigned)C) * 2u; } } } while (0)
; #define PG8_STAGE(bufoff, gbase, voff) do { _Pragma("unroll") for (int _i = 0; _i < 2; ++_i) \
;         __builtin_amdgcn_global_load_lds((const unsigned*)((const char*)(gbase) + (voff)[_i]), (LAS unsigned*)(lds + (bufoff) + ldsw + _i * 8192), 16, 0, 0); } while (0)
; #define PG8_STAGE_A1(bufoff, gbase) do { if (Epi::GATHER) PG8_STAGE(bufoff, gbase, voffA[1]); else PG8_STAGE(bufoff, (gbase) + hstep, voffA[0]); } while (0)
; #define PG8_WAIT_V(n) asm volatile("s_waitcnt vmcnt(" #n ")" ::: "memory")
; #define PG8_BAR __builtin_amdgcn_s_barrier()
; template <class Epi, class Sched>
; __device__ __forceinline__ void gemm_phase(const int tid, LAS unsigned char* lds, const bf16* Aop, const bf16* Bop, const int K_, const Sched& S, const Epi& E, const bf16* Aop1 = nullptr, const bf16* Bop1 = nullptr) {
;     ...
;     f32x4 acc[2][2][4][2];
; #pragma unroll
;     for (int a = 0; a < 2; ++a)
; #pragma unroll
;         for (int b = 0; b < 2; ++b)
; #pragma unroll
;             for (int m = 0; m < 4; ++m)
; #pragma unroll
;                 for (int n = 0; n < 2; ++n) acc[a][b][m][n] = (f32x4){0.f, 0.f, 0.f, 0.f};
;     bf16x8 At[4][2], B0[2][2], B1[2][2];
;     if (Epi::GATHER) { if (tid < 256) gtab[tid] = (unsigned)E.tok_at(cur.pm * 256 + tid); __syncthreads(); PG8_GOFFS(0); }
;     const char* cA = (const char*)((Aop1 && cur.sel) ? Aop1 : Aop) + (Epi::GATHER ? (size_t)0 : (size_t)cur.pm * tstep); const char* cB = (const char*)((Bop1 && cur.sel) ? Bop1 : Bop) + (size_t)cur.pb * tstep;
;     PG8_STAGE(PG8_SB(0, 0), cB, voffB); PG8_STAGE(PG8_SB(0, 1), cB + hstep, voffB); PG8_STAGE(PG8_SA(0, 0), cA, voffA[0]); PG8_STAGE_A1(PG8_SA(0, 1), cA);
;     if (wr == 1) PG8_BAR;
;     PG8_WAIT_V(2); PG8_BAR;
;     PG8_STAGE(PG8_SB(1, 0), cB + kstep, voffB); PG8_STAGE(PG8_SA(1, 0), cA + kstep, voffA[0]); PG8_STAGE(PG8_SB(1, 1), cB + hstep + kstep, voffB);
;     PG8_WAIT_V(6); PG8_BAR;
.LBB0_998:
	v_mov_b32_e32 v131, 0
	s_andn2_b64 vcc, exec, s[44:45]
	s_cbranch_vccnz .LBB0_1001
	s_add_u32 s12, s12, 0x80
	s_addc_u32 s13, s13, 0
	s_add_u32 s11, s26, 0x100
	v_mov_b32_e32 v4, 0
	s_addc_u32 s71, s27, 0
	s_mov_b32 s26, 0
	v_mov_b32_e32 v5, v4
	v_mov_b32_e32 v6, v4
	v_mov_b32_e32 v7, v4
	v_mov_b32_e32 v8, v4
	v_mov_b32_e32 v9, v4
	v_mov_b32_e32 v10, v4
	v_mov_b32_e32 v11, v4
	v_mov_b32_e32 v20, v4
	v_mov_b32_e32 v21, v4
	v_mov_b32_e32 v22, v4
	v_mov_b32_e32 v23, v4
	v_mov_b32_e32 v24, v4
	v_mov_b32_e32 v25, v4
	v_mov_b32_e32 v26, v4
	v_mov_b32_e32 v27, v4
	v_mov_b32_e32 v36, v4
	v_mov_b32_e32 v37, v4
	v_mov_b32_e32 v38, v4
	v_mov_b32_e32 v39, v4
	v_mov_b32_e32 v40, v4
	v_mov_b32_e32 v41, v4
	v_mov_b32_e32 v42, v4
	v_mov_b32_e32 v43, v4
	v_mov_b32_e32 v52, v4
	v_mov_b32_e32 v53, v4
	v_mov_b32_e32 v54, v4
	v_mov_b32_e32 v55, v4
	v_mov_b32_e32 v56, v4
	v_mov_b32_e32 v57, v4
	v_mov_b32_e32 v58, v4
	v_mov_b32_e32 v59, v4
	v_mov_b32_e32 v12, v4
	v_mov_b32_e32 v13, v4
	v_mov_b32_e32 v14, v4
	v_mov_b32_e32 v15, v4
	v_mov_b32_e32 v16, v4
	v_mov_b32_e32 v17, v4
	v_mov_b32_e32 v18, v4
	v_mov_b32_e32 v19, v4
	v_mov_b32_e32 v28, v4
	v_mov_b32_e32 v29, v4
	v_mov_b32_e32 v30, v4
	v_mov_b32_e32 v31, v4
	v_mov_b32_e32 v32, v4
	v_mov_b32_e32 v33, v4
	v_mov_b32_e32 v34, v4
	v_mov_b32_e32 v35, v4
	v_mov_b32_e32 v44, v4
	v_mov_b32_e32 v45, v4
	v_mov_b32_e32 v46, v4
	v_mov_b32_e32 v47, v4
	v_mov_b32_e32 v48, v4
	v_mov_b32_e32 v49, v4
	v_mov_b32_e32 v50, v4
	v_mov_b32_e32 v51, v4
	v_mov_b32_e32 v60, v4
	v_mov_b32_e32 v61, v4
	v_mov_b32_e32 v62, v4
	v_mov_b32_e32 v63, v4
	v_mov_b32_e32 v64, v4
	v_mov_b32_e32 v65, v4
	v_mov_b32_e32 v66, v4
	v_mov_b32_e32 v67, v4
	v_mov_b32_e32 v68, v4
	v_mov_b32_e32 v69, v4
	v_mov_b32_e32 v70, v4
	v_mov_b32_e32 v71, v4
	v_mov_b32_e32 v72, v4
	v_mov_b32_e32 v73, v4
	v_mov_b32_e32 v74, v4
	v_mov_b32_e32 v75, v4
	v_mov_b32_e32 v84, v4
	v_mov_b32_e32 v85, v4
	v_mov_b32_e32 v86, v4
	v_mov_b32_e32 v87, v4
	v_mov_b32_e32 v88, v4
	v_mov_b32_e32 v89, v4
	v_mov_b32_e32 v90, v4
	v_mov_b32_e32 v91, v4
	v_mov_b32_e32 v100, v4
	v_mov_b32_e32 v101, v4
	v_mov_b32_e32 v102, v4
	v_mov_b32_e32 v103, v4
	v_mov_b32_e32 v104, v4
	v_mov_b32_e32 v105, v4
	v_mov_b32_e32 v106, v4
	v_mov_b32_e32 v107, v4
	v_mov_b32_e32 v116, v4
	v_mov_b32_e32 v117, v4
	v_mov_b32_e32 v118, v4
	v_mov_b32_e32 v119, v4
	v_mov_b32_e32 v120, v4
	v_mov_b32_e32 v121, v4
	v_mov_b32_e32 v122, v4
	v_mov_b32_e32 v123, v4
	v_mov_b32_e32 v76, v4
	v_mov_b32_e32 v77, v4
	v_mov_b32_e32 v78, v4
	v_mov_b32_e32 v79, v4
	v_mov_b32_e32 v80, v4
	v_mov_b32_e32 v81, v4
	v_mov_b32_e32 v82, v4
	v_mov_b32_e32 v83, v4
	v_mov_b32_e32 v92, v4
	v_mov_b32_e32 v93, v4
	v_mov_b32_e32 v94, v4
	v_mov_b32_e32 v95, v4
	v_mov_b32_e32 v96, v4
	v_mov_b32_e32 v97, v4
	v_mov_b32_e32 v98, v4
	v_mov_b32_e32 v99, v4
	v_mov_b32_e32 v108, v4
	v_mov_b32_e32 v109, v4
	v_mov_b32_e32 v110, v4
	v_mov_b32_e32 v111, v4
	v_mov_b32_e32 v112, v4
	v_mov_b32_e32 v113, v4
	v_mov_b32_e32 v114, v4
	v_mov_b32_e32 v115, v4
	v_mov_b32_e32 v124, v4
	v_mov_b32_e32 v125, v4
	v_mov_b32_e32 v126, v4
	v_mov_b32_e32 v127, v4
	v_mov_b32_e32 v128, v4
	v_mov_b32_e32 v129, v4
	v_mov_b32_e32 v130, v4
	v_mov_b32_e32 v131, v4

; #define PG8_GOFFS(slot_) do { _Pragma("unroll") for (int _i = 0; _i < 2; ++_i) { int R, C; stage_rc(tid * 16 + _i * 8192, R, C); _Pragma("unroll") for (int _h = 0; _h < 2; ++_h) { \
;         unsigned t_ = gtab[(slot_) * 256 + R + 128 * _h]; t_ = t_ < (unsigned)(T - 1) ? t_ : (unsigned)(T - 1); voffA[_h][_i] = (t_ * (unsigned)K + (unsigned)C) * 2u; } } } while (0)
; #define PG8_STAGE(bufoff, gbase, voff) do { _Pragma("unroll") for (int _i = 0; _i < 2; ++_i) \
;         __builtin_amdgcn_global_load_lds((const unsigned*)((const char*)(gbase) + (voff)[_i]), (LAS unsigned*)(lds + (bufoff) + ldsw + _i * 8192), 16, 0, 0); } while (0)
; #define PG8_STAGE_A1(bufoff, gbase) do { if (Epi::GATHER) PG8_STAGE(bufoff, gbase, voffA[1]); else PG8_STAGE(bufoff, (gbase) + hstep, voffA[0]); } while (0)
; #define PG8_WAIT_V(n) asm volatile("s_waitcnt vmcnt(" #n ")" ::: "memory")
; #define PG8_BAR __builtin_amdgcn_s_barrier()
; template <class Epi, class Sched>
; __device__ __forceinline__ void gemm_phase(const int tid, LAS unsigned char* lds, const bf16* Aop, const bf16* Bop, const int K_, const Sched& S, const Epi& E, const bf16* Aop1 = nullptr, const bf16* Bop1 = nullptr) {
;     ...
;     f32x4 acc[2][2][4][2];
; #pragma unroll
;     for (int a = 0; a < 2; ++a)
; #pragma unroll
;         for (int b = 0; b < 2; ++b)
; #pragma unroll
;             for (int m = 0; m < 4; ++m)
; #pragma unroll
;                 for (int n = 0; n < 2; ++n) acc[a][b][m][n] = (f32x4){0.f, 0.f, 0.f, 0.f};
;     bf16x8 At[4][2], B0[2][2], B1[2][2];
;     if (Epi::GATHER) { if (tid < 256) gtab[tid] = (unsigned)E.tok_at(cur.pm * 256 + tid); __syncthreads(); PG8_GOFFS(0); }
;     const char* cA = (const char*)((Aop1 && cur.sel) ? Aop1 : Aop) + (Epi::GATHER ? (size_t)0 : (size_t)cur.pm * tstep); const char* cB = (const char*)((Bop1 && cur.sel) ? Bop1 : Bop) + (size_t)cur.pb * tstep;
;     PG8_STAGE(PG8_SB(0, 0), cB, voffB); PG8_STAGE(PG8_SB(0, 1), cB + hstep, voffB); PG8_STAGE(PG8_SA(0, 0), cA, voffA[0]); PG8_STAGE_A1(PG8_SA(0, 1), cA);
;     if (wr == 1) PG8_BAR;
;     PG8_WAIT_V(2); PG8_BAR;
;     PG8_STAGE(PG8_SB(1, 0), cB + kstep, voffB); PG8_STAGE(PG8_SA(1, 0), cA + kstep, voffA[0]); PG8_STAGE(PG8_SB(1, 1), cB + hstep + kstep, voffB);
;     PG8_WAIT_V(6); PG8_BAR;
.LBB0_1092:
	v_mov_b32_e32 v127, 0
	s_andn2_b64 vcc, exec, s[14:15]
	s_cbranch_vccnz .LBB0_1095
	s_add_u32 s34, s34, 0x80
	s_addc_u32 s35, s35, 0
	s_add_u32 s40, s36, 0x100
	v_mov_b32_e32 v4, 0
	s_addc_u32 s41, s37, 0
	s_mov_b32 s36, 0
	v_mov_b32_e32 v5, v4
	v_mov_b32_e32 v6, v4
	v_mov_b32_e32 v7, v4
	v_mov_b32_e32 v8, v4
	v_mov_b32_e32 v9, v4
	v_mov_b32_e32 v10, v4
	v_mov_b32_e32 v11, v4
	v_mov_b32_e32 v20, v4
	v_mov_b32_e32 v21, v4
	v_mov_b32_e32 v22, v4
	v_mov_b32_e32 v23, v4
	v_mov_b32_e32 v24, v4
	v_mov_b32_e32 v25, v4
	v_mov_b32_e32 v26, v4
	v_mov_b32_e32 v27, v4
	v_mov_b32_e32 v36, v4
	v_mov_b32_e32 v37, v4
	v_mov_b32_e32 v38, v4
	v_mov_b32_e32 v39, v4
	v_mov_b32_e32 v40, v4
	v_mov_b32_e32 v41, v4
	v_mov_b32_e32 v42, v4
	v_mov_b32_e32 v43, v4
	v_mov_b32_e32 v52, v4
	v_mov_b32_e32 v53, v4
	v_mov_b32_e32 v54, v4
	v_mov_b32_e32 v55, v4
	v_mov_b32_e32 v56, v4
	v_mov_b32_e32 v57, v4
	v_mov_b32_e32 v58, v4
	v_mov_b32_e32 v59, v4
	v_mov_b32_e32 v12, v4
	v_mov_b32_e32 v13, v4
	v_mov_b32_e32 v14, v4
	v_mov_b32_e32 v15, v4
	v_mov_b32_e32 v16, v4
	v_mov_b32_e32 v17, v4
	v_mov_b32_e32 v18, v4
	v_mov_b32_e32 v19, v4
	v_mov_b32_e32 v28, v4
	v_mov_b32_e32 v29, v4
	v_mov_b32_e32 v30, v4
	v_mov_b32_e32 v31, v4
	v_mov_b32_e32 v32, v4
	v_mov_b32_e32 v33, v4
	v_mov_b32_e32 v34, v4
	v_mov_b32_e32 v35, v4
	v_mov_b32_e32 v44, v4
	v_mov_b32_e32 v45, v4
	v_mov_b32_e32 v46, v4
	v_mov_b32_e32 v47, v4
	v_mov_b32_e32 v48, v4
	v_mov_b32_e32 v49, v4
	v_mov_b32_e32 v50, v4
	v_mov_b32_e32 v51, v4
	v_mov_b32_e32 v60, v4
	v_mov_b32_e32 v61, v4
	v_mov_b32_e32 v62, v4
	v_mov_b32_e32 v63, v4
	v_mov_b32_e32 v64, v4
	v_mov_b32_e32 v65, v4
	v_mov_b32_e32 v66, v4
	v_mov_b32_e32 v67, v4
	v_mov_b32_e32 v68, v4
	v_mov_b32_e32 v69, v4
	v_mov_b32_e32 v70, v4
	v_mov_b32_e32 v71, v4
	v_mov_b32_e32 v72, v4
	v_mov_b32_e32 v73, v4
	v_mov_b32_e32 v74, v4
	v_mov_b32_e32 v75, v4
	v_mov_b32_e32 v84, v4
	v_mov_b32_e32 v85, v4
	v_mov_b32_e32 v86, v4
	v_mov_b32_e32 v87, v4
	v_mov_b32_e32 v88, v4
	v_mov_b32_e32 v89, v4
	v_mov_b32_e32 v90, v4
	v_mov_b32_e32 v91, v4
	v_mov_b32_e32 v100, v4
	v_mov_b32_e32 v101, v4
	v_mov_b32_e32 v102, v4
	v_mov_b32_e32 v103, v4
	v_mov_b32_e32 v104, v4
	v_mov_b32_e32 v105, v4
	v_mov_b32_e32 v106, v4
	v_mov_b32_e32 v107, v4
	v_mov_b32_e32 v116, v4
	v_mov_b32_e32 v117, v4
	v_mov_b32_e32 v118, v4
	v_mov_b32_e32 v119, v4
	v_mov_b32_e32 v120, v4
	v_mov_b32_e32 v121, v4
	v_mov_b32_e32 v122, v4
	v_mov_b32_e32 v123, v4
	v_mov_b32_e32 v76, v4
	v_mov_b32_e32 v77, v4
	v_mov_b32_e32 v78, v4
	v_mov_b32_e32 v79, v4
	v_mov_b32_e32 v80, v4
	v_mov_b32_e32 v81, v4
	v_mov_b32_e32 v82, v4
	v_mov_b32_e32 v83, v4
	v_mov_b32_e32 v92, v4
	v_mov_b32_e32 v93, v4
	v_mov_b32_e32 v94, v4
	v_mov_b32_e32 v95, v4
	v_mov_b32_e32 v96, v4
	v_mov_b32_e32 v97, v4
	v_mov_b32_e32 v98, v4
	v_mov_b32_e32 v99, v4
	v_mov_b32_e32 v108, v4
	v_mov_b32_e32 v109, v4
	v_mov_b32_e32 v110, v4
	v_mov_b32_e32 v111, v4
	v_mov_b32_e32 v112, v4
	v_mov_b32_e32 v113, v4
	v_mov_b32_e32 v114, v4
	v_mov_b32_e32 v115, v4
	v_mov_b32_e32 v128, v4
	v_mov_b32_e32 v129, v4
	v_mov_b32_e32 v130, v4
	v_mov_b32_e32 v131, v4
	v_mov_b32_e32 v124, v4
	v_mov_b32_e32 v125, v4
	v_mov_b32_e32 v126, v4
	v_mov_b32_e32 v127, v4

; #define PG8_GOFFS(slot_) do { _Pragma("unroll") for (int _i = 0; _i < 2; ++_i) { int R, C; stage_rc(tid * 16 + _i * 8192, R, C); _Pragma("unroll") for (int _h = 0; _h < 2; ++_h) { \
;         unsigned t_ = gtab[(slot_) * 256 + R + 128 * _h]; t_ = t_ < (unsigned)(T - 1) ? t_ : (unsigned)(T - 1); voffA[_h][_i] = (t_ * (unsigned)K + (unsigned)C) * 2u; } } } while (0)
; #define PG8_STAGE(bufoff, gbase, voff) do { _Pragma("unroll") for (int _i = 0; _i < 2; ++_i) \
;         __builtin_amdgcn_global_load_lds((const unsigned*)((const char*)(gbase) + (voff)[_i]), (LAS unsigned*)(lds + (bufoff) + ldsw + _i * 8192), 16, 0, 0); } while (0)
; #define PG8_STAGE_A1(bufoff, gbase) do { if (Epi::GATHER) PG8_STAGE(bufoff, gbase, voffA[1]); else PG8_STAGE(bufoff, (gbase) + hstep, voffA[0]); } while (0)
; #define PG8_WAIT_V(n) asm volatile("s_waitcnt vmcnt(" #n ")" ::: "memory")
; #define PG8_BAR __builtin_amdgcn_s_barrier()
; template <class Epi, class Sched>
; __device__ __forceinline__ void gemm_phase(const int tid, LAS unsigned char* lds, const bf16* Aop, const bf16* Bop, const int K_, const Sched& S, const Epi& E, const bf16* Aop1 = nullptr, const bf16* Bop1 = nullptr) {
;     ...
;     f32x4 acc[2][2][4][2];
; #pragma unroll
;     for (int a = 0; a < 2; ++a)
; #pragma unroll
;         for (int b = 0; b < 2; ++b)
; #pragma unroll
;             for (int m = 0; m < 4; ++m)
; #pragma unroll
;                 for (int n = 0; n < 2; ++n) acc[a][b][m][n] = (f32x4){0.f, 0.f, 0.f, 0.f};
;     bf16x8 At[4][2], B0[2][2], B1[2][2];
;     if (Epi::GATHER) { if (tid < 256) gtab[tid] = (unsigned)E.tok_at(cur.pm * 256 + tid); __syncthreads(); PG8_GOFFS(0); }
;     const char* cA = (const char*)((Aop1 && cur.sel) ? Aop1 : Aop) + (Epi::GATHER ? (size_t)0 : (size_t)cur.pm * tstep); const char* cB = (const char*)((Bop1 && cur.sel) ? Bop1 : Bop) + (size_t)cur.pb * tstep;
;     PG8_STAGE(PG8_SB(0, 0), cB, voffB); PG8_STAGE(PG8_SB(0, 1), cB + hstep, voffB); PG8_STAGE(PG8_SA(0, 0), cA, voffA[0]); PG8_STAGE_A1(PG8_SA(0, 1), cA);
;     if (wr == 1) PG8_BAR;
;     PG8_WAIT_V(2); PG8_BAR;
;     PG8_STAGE(PG8_SB(1, 0), cB + kstep, voffB); PG8_STAGE(PG8_SA(1, 0), cA + kstep, voffA[0]); PG8_STAGE(PG8_SB(1, 1), cB + hstep + kstep, voffB);
;     PG8_WAIT_V(6); PG8_BAR;
.LBB0_1398:
	v_mov_b32_e32 v127, 0
	s_andn2_b64 vcc, exec, s[16:17]
	s_cbranch_vccnz .LBB0_1401
	s_add_u32 s34, s34, 0x80
	s_addc_u32 s35, s35, 0
	s_add_u32 s65, s36, 0x100
	v_mov_b32_e32 v4, 0
	s_addc_u32 s66, s37, 0
	s_mov_b32 s36, 0
	v_mov_b32_e32 v5, v4
	v_mov_b32_e32 v6, v4
	v_mov_b32_e32 v7, v4
	v_mov_b32_e32 v8, v4
	v_mov_b32_e32 v9, v4
	v_mov_b32_e32 v10, v4
	v_mov_b32_e32 v11, v4
	v_mov_b32_e32 v20, v4
	v_mov_b32_e32 v21, v4
	v_mov_b32_e32 v22, v4
	v_mov_b32_e32 v23, v4
	v_mov_b32_e32 v24, v4
	v_mov_b32_e32 v25, v4
	v_mov_b32_e32 v26, v4
	v_mov_b32_e32 v27, v4
	v_mov_b32_e32 v36, v4
	v_mov_b32_e32 v37, v4
	v_mov_b32_e32 v38, v4
	v_mov_b32_e32 v39, v4
	v_mov_b32_e32 v40, v4
	v_mov_b32_e32 v41, v4
	v_mov_b32_e32 v42, v4
	v_mov_b32_e32 v43, v4
	v_mov_b32_e32 v52, v4
	v_mov_b32_e32 v53, v4
	v_mov_b32_e32 v54, v4
	v_mov_b32_e32 v55, v4
	v_mov_b32_e32 v56, v4
	v_mov_b32_e32 v57, v4
	v_mov_b32_e32 v58, v4
	v_mov_b32_e32 v59, v4
	v_mov_b32_e32 v12, v4
	v_mov_b32_e32 v13, v4
	v_mov_b32_e32 v14, v4
	v_mov_b32_e32 v15, v4
	v_mov_b32_e32 v16, v4
	v_mov_b32_e32 v17, v4
	v_mov_b32_e32 v18, v4
	v_mov_b32_e32 v19, v4
	v_mov_b32_e32 v28, v4
	v_mov_b32_e32 v29, v4
	v_mov_b32_e32 v30, v4
	v_mov_b32_e32 v31, v4
	v_mov_b32_e32 v32, v4
	v_mov_b32_e32 v33, v4
	v_mov_b32_e32 v34, v4
	v_mov_b32_e32 v35, v4
	v_mov_b32_e32 v44, v4
	v_mov_b32_e32 v45, v4
	v_mov_b32_e32 v46, v4
	v_mov_b32_e32 v47, v4
	v_mov_b32_e32 v48, v4
	v_mov_b32_e32 v49, v4
	v_mov_b32_e32 v50, v4
	v_mov_b32_e32 v51, v4
	v_mov_b32_e32 v60, v4
	v_mov_b32_e32 v61, v4
	v_mov_b32_e32 v62, v4
	v_mov_b32_e32 v63, v4
	v_mov_b32_e32 v64, v4
	v_mov_b32_e32 v65, v4
	v_mov_b32_e32 v66, v4
	v_mov_b32_e32 v67, v4
	v_mov_b32_e32 v68, v4
	v_mov_b32_e32 v69, v4
	v_mov_b32_e32 v70, v4
	v_mov_b32_e32 v71, v4
	v_mov_b32_e32 v72, v4
	v_mov_b32_e32 v73, v4
	v_mov_b32_e32 v74, v4
	v_mov_b32_e32 v75, v4
	v_mov_b32_e32 v84, v4
	v_mov_b32_e32 v85, v4
	v_mov_b32_e32 v86, v4
	v_mov_b32_e32 v87, v4
	v_mov_b32_e32 v88, v4
	v_mov_b32_e32 v89, v4
	v_mov_b32_e32 v90, v4
	v_mov_b32_e32 v91, v4
	v_mov_b32_e32 v100, v4
	v_mov_b32_e32 v101, v4
	v_mov_b32_e32 v102, v4
	v_mov_b32_e32 v103, v4
	v_mov_b32_e32 v104, v4
	v_mov_b32_e32 v105, v4
	v_mov_b32_e32 v106, v4
	v_mov_b32_e32 v107, v4
	v_mov_b32_e32 v116, v4
	v_mov_b32_e32 v117, v4
	v_mov_b32_e32 v118, v4
	v_mov_b32_e32 v119, v4
	v_mov_b32_e32 v120, v4
	v_mov_b32_e32 v121, v4
	v_mov_b32_e32 v122, v4
	v_mov_b32_e32 v123, v4
	v_mov_b32_e32 v76, v4
	v_mov_b32_e32 v77, v4
	v_mov_b32_e32 v78, v4
	v_mov_b32_e32 v79, v4
	v_mov_b32_e32 v80, v4
	v_mov_b32_e32 v81, v4
	v_mov_b32_e32 v82, v4
	v_mov_b32_e32 v83, v4
	v_mov_b32_e32 v92, v4
	v_mov_b32_e32 v93, v4
	v_mov_b32_e32 v94, v4
	v_mov_b32_e32 v95, v4
	v_mov_b32_e32 v96, v4
	v_mov_b32_e32 v97, v4
	v_mov_b32_e32 v98, v4
	v_mov_b32_e32 v99, v4
	v_mov_b32_e32 v108, v4
	v_mov_b32_e32 v109, v4
	v_mov_b32_e32 v110, v4
	v_mov_b32_e32 v111, v4
	v_mov_b32_e32 v112, v4
	v_mov_b32_e32 v113, v4
	v_mov_b32_e32 v114, v4
	v_mov_b32_e32 v115, v4
	v_mov_b32_e32 v128, v4
	v_mov_b32_e32 v129, v4
	v_mov_b32_e32 v130, v4
	v_mov_b32_e32 v131, v4
	v_mov_b32_e32 v124, v4
	v_mov_b32_e32 v125, v4
	v_mov_b32_e32 v126, v4
	v_mov_b32_e32 v127, v4

; #define PG8_GOFFS(slot_) do { _Pragma("unroll") for (int _i = 0; _i < 2; ++_i) { int R, C; stage_rc(tid * 16 + _i * 8192, R, C); _Pragma("unroll") for (int _h = 0; _h < 2; ++_h) { \
;         unsigned t_ = gtab[(slot_) * 256 + R + 128 * _h]; t_ = t_ < (unsigned)(T - 1) ? t_ : (unsigned)(T - 1); voffA[_h][_i] = (t_ * (unsigned)K + (unsigned)C) * 2u; } } } while (0)
; #define PG8_STAGE(bufoff, gbase, voff) do { _Pragma("unroll") for (int _i = 0; _i < 2; ++_i) \
;         __builtin_amdgcn_global_load_lds((const unsigned*)((const char*)(gbase) + (voff)[_i]), (LAS unsigned*)(lds + (bufoff) + ldsw + _i * 8192), 16, 0, 0); } while (0)
; #define PG8_STAGE_A1(bufoff, gbase) do { if (Epi::GATHER) PG8_STAGE(bufoff, gbase, voffA[1]); else PG8_STAGE(bufoff, (gbase) + hstep, voffA[0]); } while (0)
; #define PG8_WAIT_V(n) asm volatile("s_waitcnt vmcnt(" #n ")" ::: "memory")
; #define PG8_BAR __builtin_amdgcn_s_barrier()
; template <class Epi, class Sched>
; __device__ __forceinline__ void gemm_phase(const int tid, LAS unsigned char* lds, const bf16* Aop, const bf16* Bop, const int K_, const Sched& S, const Epi& E, const bf16* Aop1 = nullptr, const bf16* Bop1 = nullptr) {
;     ...
;     f32x4 acc[2][2][4][2];
; #pragma unroll
;     for (int a = 0; a < 2; ++a)
; #pragma unroll
;         for (int b = 0; b < 2; ++b)
; #pragma unroll
;             for (int m = 0; m < 4; ++m)
; #pragma unroll
;                 for (int n = 0; n < 2; ++n) acc[a][b][m][n] = (f32x4){0.f, 0.f, 0.f, 0.f};
;     bf16x8 At[4][2], B0[2][2], B1[2][2];
;     if (Epi::GATHER) { if (tid < 256) gtab[tid] = (unsigned)E.tok_at(cur.pm * 256 + tid); __syncthreads(); PG8_GOFFS(0); }
;     const char* cA = (const char*)((Aop1 && cur.sel) ? Aop1 : Aop) + (Epi::GATHER ? (size_t)0 : (size_t)cur.pm * tstep); const char* cB = (const char*)((Bop1 && cur.sel) ? Bop1 : Bop) + (size_t)cur.pb * tstep;
;     PG8_STAGE(PG8_SB(0, 0), cB, voffB); PG8_STAGE(PG8_SB(0, 1), cB + hstep, voffB); PG8_STAGE(PG8_SA(0, 0), cA, voffA[0]); PG8_STAGE_A1(PG8_SA(0, 1), cA);
;     if (wr == 1) PG8_BAR;
;     PG8_WAIT_V(2); PG8_BAR;
;     PG8_STAGE(PG8_SB(1, 0), cB + kstep, voffB); PG8_STAGE(PG8_SA(1, 0), cA + kstep, voffA[0]); PG8_STAGE(PG8_SB(1, 1), cB + hstep + kstep, voffB);
;     PG8_WAIT_V(6); PG8_BAR;
.LBB0_1418:
	v_mov_b32_e32 v127, 0
	s_andn2_b64 vcc, exec, s[16:17]
	s_cbranch_vccnz .LBB0_1421
	s_add_u32 s34, s34, 0x80
	s_addc_u32 s35, s35, 0
	s_add_u32 s15, s36, 0x100
	v_mov_b32_e32 v4, 0
	s_addc_u32 s67, s37, 0
	s_mov_b32 s36, 0
	v_mov_b32_e32 v5, v4
	v_mov_b32_e32 v6, v4
	v_mov_b32_e32 v7, v4
	v_mov_b32_e32 v8, v4
	v_mov_b32_e32 v9, v4
	v_mov_b32_e32 v10, v4
	v_mov_b32_e32 v11, v4
	v_mov_b32_e32 v20, v4
	v_mov_b32_e32 v21, v4
	v_mov_b32_e32 v22, v4
	v_mov_b32_e32 v23, v4
	v_mov_b32_e32 v24, v4
	v_mov_b32_e32 v25, v4
	v_mov_b32_e32 v26, v4
	v_mov_b32_e32 v27, v4
	v_mov_b32_e32 v36, v4
	v_mov_b32_e32 v37, v4
	v_mov_b32_e32 v38, v4
	v_mov_b32_e32 v39, v4
	v_mov_b32_e32 v40, v4
	v_mov_b32_e32 v41, v4
	v_mov_b32_e32 v42, v4
	v_mov_b32_e32 v43, v4
	v_mov_b32_e32 v52, v4
	v_mov_b32_e32 v53, v4
	v_mov_b32_e32 v54, v4
	v_mov_b32_e32 v55, v4
	v_mov_b32_e32 v56, v4
	v_mov_b32_e32 v57, v4
	v_mov_b32_e32 v58, v4
	v_mov_b32_e32 v59, v4
	v_mov_b32_e32 v12, v4
	v_mov_b32_e32 v13, v4
	v_mov_b32_e32 v14, v4
	v_mov_b32_e32 v15, v4
	v_mov_b32_e32 v16, v4
	v_mov_b32_e32 v17, v4
	v_mov_b32_e32 v18, v4
	v_mov_b32_e32 v19, v4
	v_mov_b32_e32 v28, v4
	v_mov_b32_e32 v29, v4
	v_mov_b32_e32 v30, v4
	v_mov_b32_e32 v31, v4
	v_mov_b32_e32 v32, v4
	v_mov_b32_e32 v33, v4
	v_mov_b32_e32 v34, v4
	v_mov_b32_e32 v35, v4
	v_mov_b32_e32 v44, v4
	v_mov_b32_e32 v45, v4
	v_mov_b32_e32 v46, v4
	v_mov_b32_e32 v47, v4
	v_mov_b32_e32 v48, v4
	v_mov_b32_e32 v49, v4
	v_mov_b32_e32 v50, v4
	v_mov_b32_e32 v51, v4
	v_mov_b32_e32 v60, v4
	v_mov_b32_e32 v61, v4
	v_mov_b32_e32 v62, v4
	v_mov_b32_e32 v63, v4
	v_mov_b32_e32 v64, v4
	v_mov_b32_e32 v65, v4
	v_mov_b32_e32 v66, v4
	v_mov_b32_e32 v67, v4
	v_mov_b32_e32 v68, v4
	v_mov_b32_e32 v69, v4
	v_mov_b32_e32 v70, v4
	v_mov_b32_e32 v71, v4
	v_mov_b32_e32 v72, v4
	v_mov_b32_e32 v73, v4
	v_mov_b32_e32 v74, v4
	v_mov_b32_e32 v75, v4
	v_mov_b32_e32 v84, v4
	v_mov_b32_e32 v85, v4
	v_mov_b32_e32 v86, v4
	v_mov_b32_e32 v87, v4
	v_mov_b32_e32 v88, v4
	v_mov_b32_e32 v89, v4
	v_mov_b32_e32 v90, v4
	v_mov_b32_e32 v91, v4
	v_mov_b32_e32 v100, v4
	v_mov_b32_e32 v101, v4
	v_mov_b32_e32 v102, v4
	v_mov_b32_e32 v103, v4
	v_mov_b32_e32 v104, v4
	v_mov_b32_e32 v105, v4
	v_mov_b32_e32 v106, v4
	v_mov_b32_e32 v107, v4
	v_mov_b32_e32 v116, v4
	v_mov_b32_e32 v117, v4
	v_mov_b32_e32 v118, v4
	v_mov_b32_e32 v119, v4
	v_mov_b32_e32 v120, v4
	v_mov_b32_e32 v121, v4
	v_mov_b32_e32 v122, v4
	v_mov_b32_e32 v123, v4
	v_mov_b32_e32 v76, v4
	v_mov_b32_e32 v77, v4
	v_mov_b32_e32 v78, v4
	v_mov_b32_e32 v79, v4
	v_mov_b32_e32 v80, v4
	v_mov_b32_e32 v81, v4
	v_mov_b32_e32 v82, v4
	v_mov_b32_e32 v83, v4
	v_mov_b32_e32 v92, v4
	v_mov_b32_e32 v93, v4
	v_mov_b32_e32 v94, v4
	v_mov_b32_e32 v95, v4
	v_mov_b32_e32 v96, v4
	v_mov_b32_e32 v97, v4
	v_mov_b32_e32 v98, v4
	v_mov_b32_e32 v99, v4
	v_mov_b32_e32 v108, v4
	v_mov_b32_e32 v109, v4
	v_mov_b32_e32 v110, v4
	v_mov_b32_e32 v111, v4
	v_mov_b32_e32 v112, v4
	v_mov_b32_e32 v113, v4
	v_mov_b32_e32 v114, v4
	v_mov_b32_e32 v115, v4
	v_mov_b32_e32 v128, v4
	v_mov_b32_e32 v129, v4
	v_mov_b32_e32 v130, v4
	v_mov_b32_e32 v131, v4
	v_mov_b32_e32 v124, v4
	v_mov_b32_e32 v125, v4
	v_mov_b32_e32 v126, v4
	v_mov_b32_e32 v127, v4

; #define PG8_GOFFS(slot_) do { _Pragma("unroll") for (int _i = 0; _i < 2; ++_i) { int R, C; stage_rc(tid * 16 + _i * 8192, R, C); _Pragma("unroll") for (int _h = 0; _h < 2; ++_h) { \
;         unsigned t_ = gtab[(slot_) * 256 + R + 128 * _h]; t_ = t_ < (unsigned)(T - 1) ? t_ : (unsigned)(T - 1); voffA[_h][_i] = (t_ * (unsigned)K + (unsigned)C) * 2u; } } } while (0)
; #define PG8_STAGE(bufoff, gbase, voff) do { _Pragma("unroll") for (int _i = 0; _i < 2; ++_i) \
;         __builtin_amdgcn_global_load_lds((const unsigned*)((const char*)(gbase) + (voff)[_i]), (LAS unsigned*)(lds + (bufoff) + ldsw + _i * 8192), 16, 0, 0); } while (0)
; #define PG8_STAGE_A1(bufoff, gbase) do { if (Epi::GATHER) PG8_STAGE(bufoff, gbase, voffA[1]); else PG8_STAGE(bufoff, (gbase) + hstep, voffA[0]); } while (0)
; #define PG8_WAIT_V(n) asm volatile("s_waitcnt vmcnt(" #n ")" ::: "memory")
; #define PG8_BAR __builtin_amdgcn_s_barrier()
; template <class Epi, class Sched>
; __device__ __forceinline__ void gemm_phase(const int tid, LAS unsigned char* lds, const bf16* Aop, const bf16* Bop, const int K_, const Sched& S, const Epi& E, const bf16* Aop1 = nullptr, const bf16* Bop1 = nullptr) {
;     ...
;     f32x4 acc[2][2][4][2];
; #pragma unroll
;     for (int a = 0; a < 2; ++a)
; #pragma unroll
;         for (int b = 0; b < 2; ++b)
; #pragma unroll
;             for (int m = 0; m < 4; ++m)
; #pragma unroll
;                 for (int n = 0; n < 2; ++n) acc[a][b][m][n] = (f32x4){0.f, 0.f, 0.f, 0.f};
;     bf16x8 At[4][2], B0[2][2], B1[2][2];
;     if (Epi::GATHER) { if (tid < 256) gtab[tid] = (unsigned)E.tok_at(cur.pm * 256 + tid); __syncthreads(); PG8_GOFFS(0); }
;     const char* cA = (const char*)((Aop1 && cur.sel) ? Aop1 : Aop) + (Epi::GATHER ? (size_t)0 : (size_t)cur.pm * tstep); const char* cB = (const char*)((Bop1 && cur.sel) ? Bop1 : Bop) + (size_t)cur.pb * tstep;
;     PG8_STAGE(PG8_SB(0, 0), cB, voffB); PG8_STAGE(PG8_SB(0, 1), cB + hstep, voffB); PG8_STAGE(PG8_SA(0, 0), cA, voffA[0]); PG8_STAGE_A1(PG8_SA(0, 1), cA);
;     if (wr == 1) PG8_BAR;
;     PG8_WAIT_V(2); PG8_BAR;
;     PG8_STAGE(PG8_SB(1, 0), cB + kstep, voffB); PG8_STAGE(PG8_SA(1, 0), cA + kstep, voffA[0]); PG8_STAGE(PG8_SB(1, 1), cB + hstep + kstep, voffB);
;     PG8_WAIT_V(6); PG8_BAR;
.LBB0_1595:
	v_mov_b32_e32 v131, 0
	s_andn2_b64 vcc, exec, s[64:65]
	s_cbranch_vccnz .LBB0_1598
	s_add_u32 s2, s2, 0x80
	s_addc_u32 s3, s3, 0
	s_add_u32 s6, s4, 0x100
	v_mov_b32_e32 v4, 0
	s_addc_u32 s7, s5, 0
	s_mov_b32 s4, 0
	v_mov_b32_e32 v5, v4
	v_mov_b32_e32 v6, v4
	v_mov_b32_e32 v7, v4
	v_mov_b32_e32 v8, v4
	v_mov_b32_e32 v9, v4
	v_mov_b32_e32 v10, v4
	v_mov_b32_e32 v11, v4
	v_mov_b32_e32 v20, v4
	v_mov_b32_e32 v21, v4
	v_mov_b32_e32 v22, v4
	v_mov_b32_e32 v23, v4
	v_mov_b32_e32 v24, v4
	v_mov_b32_e32 v25, v4
	v_mov_b32_e32 v26, v4
	v_mov_b32_e32 v27, v4
	v_mov_b32_e32 v36, v4
	v_mov_b32_e32 v37, v4
	v_mov_b32_e32 v38, v4
	v_mov_b32_e32 v39, v4
	v_mov_b32_e32 v40, v4
	v_mov_b32_e32 v41, v4
	v_mov_b32_e32 v42, v4
	v_mov_b32_e32 v43, v4
	v_mov_b32_e32 v52, v4
	v_mov_b32_e32 v53, v4
	v_mov_b32_e32 v54, v4
	v_mov_b32_e32 v55, v4
	v_mov_b32_e32 v56, v4
	v_mov_b32_e32 v57, v4
	v_mov_b32_e32 v58, v4
	v_mov_b32_e32 v59, v4
	v_mov_b32_e32 v12, v4
	v_mov_b32_e32 v13, v4
	v_mov_b32_e32 v14, v4
	v_mov_b32_e32 v15, v4
	v_mov_b32_e32 v16, v4
	v_mov_b32_e32 v17, v4
	v_mov_b32_e32 v18, v4
	v_mov_b32_e32 v19, v4
	v_mov_b32_e32 v28, v4
	v_mov_b32_e32 v29, v4
	v_mov_b32_e32 v30, v4
	v_mov_b32_e32 v31, v4
	v_mov_b32_e32 v32, v4
	v_mov_b32_e32 v33, v4
	v_mov_b32_e32 v34, v4
	v_mov_b32_e32 v35, v4
	v_mov_b32_e32 v44, v4
	v_mov_b32_e32 v45, v4
	v_mov_b32_e32 v46, v4
	v_mov_b32_e32 v47, v4
	v_mov_b32_e32 v48, v4
	v_mov_b32_e32 v49, v4
	v_mov_b32_e32 v50, v4
	v_mov_b32_e32 v51, v4
	v_mov_b32_e32 v60, v4
	v_mov_b32_e32 v61, v4
	v_mov_b32_e32 v62, v4
	v_mov_b32_e32 v63, v4
	v_mov_b32_e32 v64, v4
	v_mov_b32_e32 v65, v4
	v_mov_b32_e32 v66, v4
	v_mov_b32_e32 v67, v4
	v_mov_b32_e32 v68, v4
	v_mov_b32_e32 v69, v4
	v_mov_b32_e32 v70, v4
	v_mov_b32_e32 v71, v4
	v_mov_b32_e32 v72, v4
	v_mov_b32_e32 v73, v4
	v_mov_b32_e32 v74, v4
	v_mov_b32_e32 v75, v4
	v_mov_b32_e32 v84, v4
	v_mov_b32_e32 v85, v4
	v_mov_b32_e32 v86, v4
	v_mov_b32_e32 v87, v4
	v_mov_b32_e32 v88, v4
	v_mov_b32_e32 v89, v4
	v_mov_b32_e32 v90, v4
	v_mov_b32_e32 v91, v4
	v_mov_b32_e32 v100, v4
	v_mov_b32_e32 v101, v4
	v_mov_b32_e32 v102, v4
	v_mov_b32_e32 v103, v4
	v_mov_b32_e32 v104, v4
	v_mov_b32_e32 v105, v4
	v_mov_b32_e32 v106, v4
	v_mov_b32_e32 v107, v4
	v_mov_b32_e32 v116, v4
	v_mov_b32_e32 v117, v4
	v_mov_b32_e32 v118, v4
	v_mov_b32_e32 v119, v4
	v_mov_b32_e32 v120, v4
	v_mov_b32_e32 v121, v4
	v_mov_b32_e32 v122, v4
	v_mov_b32_e32 v123, v4
	v_mov_b32_e32 v76, v4
	v_mov_b32_e32 v77, v4
	v_mov_b32_e32 v78, v4
	v_mov_b32_e32 v79, v4
	v_mov_b32_e32 v80, v4
	v_mov_b32_e32 v81, v4
	v_mov_b32_e32 v82, v4
	v_mov_b32_e32 v83, v4
	v_mov_b32_e32 v92, v4
	v_mov_b32_e32 v93, v4
	v_mov_b32_e32 v94, v4
	v_mov_b32_e32 v95, v4
	v_mov_b32_e32 v96, v4
	v_mov_b32_e32 v97, v4
	v_mov_b32_e32 v98, v4
	v_mov_b32_e32 v99, v4
	v_mov_b32_e32 v108, v4
	v_mov_b32_e32 v109, v4
	v_mov_b32_e32 v110, v4
	v_mov_b32_e32 v111, v4
	v_mov_b32_e32 v112, v4
	v_mov_b32_e32 v113, v4
	v_mov_b32_e32 v114, v4
	v_mov_b32_e32 v115, v4
	v_mov_b32_e32 v124, v4
	v_mov_b32_e32 v125, v4
	v_mov_b32_e32 v126, v4
	v_mov_b32_e32 v127, v4
	v_mov_b32_e32 v128, v4
	v_mov_b32_e32 v129, v4
	v_mov_b32_e32 v130, v4
	v_mov_b32_e32 v131, v4
